# plus XCC placement word read deferred behind the first PA tile prologue wait
# speedup vs baseline: 1.0085x; 1.0005x over previous
;     __device__ bool next(int i, Unit& u) const {
;         const long L = (long)i * G + c; if (L >= nwg) return false;
;         int wgid = (int)L; { const int q = nwg / NXCD, r = nwg % NXCD, xcd = wgid % NXCD, off = wgid / NXCD; wgid = (xcd < r ? xcd * (q + 1) : r * (q + 1) + (xcd - r) * q) + off; }
;         const int nig = WGM * nN, gid = wgid / nig, fm = gid * WGM, gsz = (nM - fm) < WGM ? (nM - fm) : WGM;
;         u.pm = fm + ((wgid % nig) % gsz); u.pn = (wgid % nig) / gsz; return true;
.LBB0_160:
	s_cmp_lt_i32 s66, 2
	s_cselect_b64 s[4:5], -1, 0
	s_and_b64 s[6:7], s[4:5], s[0:1]
	s_andn2_b64 vcc, exec, s[6:7]
	s_cbranch_vccnz .LBB0_212
	s_and_b32 s100, s2, 7
	s_lshl_b32 s100, s100, 7
	s_add_u32 s100, s100, s92
	s_addc_u32 s101, s93, 0
	s_add_u32 s100, s100, 0x3c00
	s_addc_u32 s101, s101, 0
	v_mov_b32_e32 v254, 0
	global_load_dword v255, v254, s[100:101] sc1
	s_mov_b32 s99, -1
	s_cmpk_lt_i32 s2, 0xfc0
	s_cselect_b64 s[0:1], -1, 0
	s_cmpk_gt_i32 s2, 0xfbf
	v_readfirstlane_b32 s4, v190
	s_cbranch_scc1 .LBB0_163
	s_ashr_i32 s5, s2, 31
	s_lshr_b32 s5, s5, 29
	s_add_i32 s5, s2, s5
	s_ashr_i32 s8, s5, 3
	s_and_b32 s5, s5, -8
	s_sub_i32 s5, s2, s5
	s_cmp_lt_i32 s5, 0
	s_movk_i32 s9, 0x1f9
	s_cselect_b32 s9, s9, 0x1f8
	s_mul_i32 s5, s5, s9
	s_add_i32 s5, s5, s8
	s_mul_hi_i32 s8, s5, 0x30c30c31
	s_lshr_b32 s9, s8, 31
	s_ashr_i32 s8, s8, 4
	s_add_i32 s8, s8, s9
	s_lshl_b32 s9, s8, 2
	s_mulk_i32 s8, 0x54
	s_sub_i32 s5, s5, s8
	s_bfe_i32 s8, s5, 0x80000
	s_bfe_u32 s8, s8, 0x2000d
	s_add_i32 s8, s5, s8
	s_bfe_i32 s10, s8, 0x80000
	s_and_b32 s8, s8, 0xfc
	s_sub_i32 s5, s5, s8
	s_sext_i32_i16 s10, s10
	s_sext_i32_i8 s5, s5
	s_add_i32 s8, s9, s5
	s_ashr_i32 s38, s10, 2
	s_mul_i32 s100, s8, 0xaab
	s_lshr_b32 s100, s100, 16
	s_mul_i32 s101, s100, 24
	s_sub_i32 s101, s8, s101
	s_lshl_b32 s101, s101, 3
	s_or_b32 s8, s101, s100

; #define PG8_STAGE(bufoff, gbase, voff) do { _Pragma("unroll") for (int _i = 0; _i < 2; ++_i) \
;         __builtin_amdgcn_global_load_lds((const unsigned*)((const char*)(gbase) + (voff)[_i]), (LAS unsigned*)(lds + (bufoff) + ldsw + _i * 8192), 16, 0, 0); } while (0)
; #define PG8_WAIT_V(n) asm volatile("s_waitcnt vmcnt(" #n ")" ::: "memory")
; #define PG8_BAR __builtin_amdgcn_s_barrier()
; template <class Epi, class Sched>
; __device__ __forceinline__ void gemm_phase(LAS unsigned char* lds, const Sched& S, const Epi& E, bool natural = false) {
;     ...
;     PG8_STAGE(PG8_SB(0, 0), cB, voffB0); PG8_STAGE(PG8_SB(0, 1), cB, voffB1); PG8_STAGE(PG8_SA(0, 0), cA, voffA); PG8_STAGE(PG8_SA(0, 1), cA + hstep, voffA);
;     if (wr == 1) PG8_BAR;
;     PG8_WAIT_V(2); PG8_BAR;
;     PG8_STAGE(PG8_SB(1, 0), cB + kstep, voffB0); PG8_STAGE(PG8_SA(1, 0), cA + kstep, voffA); PG8_STAGE(PG8_SB(1, 1), cB + kstep, voffB1);
;     PG8_WAIT_V(6); PG8_BAR;
.LBB0_166:
	s_waitcnt vmcnt(0)
	v_readfirstlane_b32 s32, v255
	s_nop 0
	s_bcnt1_i32_b32 s32, s32
	v_and_b32_e32 v13, 15, v190
	v_lshlrev_b32_e32 v12, 1, v152
	v_lshlrev_b32_e32 v14, 2, v190
	s_and_b32 s5, s0, 3
	v_lshl_or_b32 v153, s1, 6, v13
	v_lshl_or_b32 v13, v13, 6, v12
	s_lshl_b32 s0, s1, 13
	v_and_b32_e32 v14, 32, v14
	v_bitop3_b32 v15, v13, s0, v14 bitop3:0xde
	v_lshlrev_b32_e32 v13, 6, v190
	s_movk_i32 s0, 0x3c0
	s_lshl_b32 s14, s5, 12
	v_and_or_b32 v13, v13, s0, v12
	s_mov_b64 s[12:13], 0x80
	s_add_u32 s0, s42, 0x80
	s_addc_u32 s1, s43, 0
	s_add_i32 m0, s39, 0x18000
	v_lshl_add_u64 v[4:5], v[4:5], 0, s[12:13]
	s_waitcnt vmcnt(2)
	s_barrier
	global_load_lds_dwordx4 v[4:5], off
	v_lshl_add_u64 v[0:1], v[0:1], 0, s[12:13]
	s_add_i32 m0, s39, 0x1a000
	s_add_i32 s51, s39, 0x8000
	global_load_lds_dwordx4 v[0:1], off
	v_lshl_add_u64 v[0:1], v[2:3], 0, s[12:13]
	s_mov_b32 m0, s51
	s_add_i32 s52, s39, 0xa000
	global_load_lds_dwordx4 v[0:1], off
	v_lshl_add_u64 v[0:1], v[6:7], 0, s[12:13]
	s_mov_b32 m0, s52
	v_bitop3_b32 v192, s14, v13, v14 bitop3:0xf6
	global_load_lds_dwordx4 v[0:1], off
	s_add_i32 m0, s39, 0x1c000
	v_lshl_add_u64 v[0:1], s[0:1], 0, v[158:159]
	global_load_lds_dwordx4 v[0:1], off
	v_lshl_add_u64 v[0:1], s[0:1], 0, v[164:165]
	s_add_i32 m0, s39, 0x1e000
	s_cmpk_lt_u32 s4, 0x100
	global_load_lds_dwordx4 v[0:1], off
	s_cselect_b64 s[14:15], -1, 0
	s_lshl_b32 s53, s5, 6
	s_cmp_gt_u32 s5, 1
	s_waitcnt lgkmcnt(0)
	s_cselect_b64 s[80:81], -1, 0
	v_and_b32_e32 v0, 7, v190
	s_or_b32 s54, s53, 0xfffffc00
	s_or_b32 s55, s53, 0xfffffe00
	s_ashr_i32 s56, s50, 31
	s_ashr_i32 s57, s2, 31
	v_lshl_or_b32 v1, s5, 5, v152
	v_or_b32_e32 v194, s53, v152
	s_add_u32 s82, s64, 0x16100000
	v_or_b32_e32 v195, 0xfffffa80, v1
	v_lshlrev_b32_e32 v0, 1, v0
	v_mov_b32_e32 v1, v167
	v_add_u32_e32 v166, 0xffffff80, v194
	s_addc_u32 s83, s65, 0
	v_lshl_add_u64 v[0:1], s[64:65], 0, v[0:1]
	s_add_u32 s96, s62, 0x6000000
	v_lshl_add_u64 v[0:1], v[166:167], 4, v[0:1]
	s_mov_b64 s[0:1], 0x19d00000
	s_addc_u32 s97, s63, 0
	v_lshl_add_u64 v[168:169], v[0:1], 0, s[0:1]
	s_lshl_b32 s0, s5, 7
	s_add_u32 s0, s64, s0
	s_addc_u32 s1, s65, 0
	v_mov_b32_e32 v13, v167
	v_lshl_add_u64 v[0:1], s[0:1], 0, v[12:13]
	s_mov_b64 s[0:1], 0x19100000
	v_lshl_add_u64 v[170:171], v[0:1], 0, s[0:1]
	v_lshl_add_u64 v[0:1], s[64:65], 0, v[12:13]
	s_mov_b64 s[0:1], 0xd100000
	v_lshl_add_u64 v[172:173], v[0:1], 0, s[0:1]
	s_mov_b64 s[0:1], 0xa100000
	v_lshl_add_u64 v[174:175], v[0:1], 0, s[0:1]
	s_mov_b64 s[0:1], 0x7100000
	v_lshl_add_u64 v[176:177], v[0:1], 0, s[0:1]
	v_lshlrev_b32_e32 v0, 8, v190
	v_and_b32_e32 v0, 0x38000, v0
	v_lshlrev_b32_e32 v1, 11, v10
	v_or3_b32 v0, v8, v0, v1
	v_add_u32_e32 v178, v0, v9
	v_lshlrev_b32_e32 v0, 4, v11
	v_and_b32_e32 v0, 0x78000, v0
	s_waitcnt vmcnt(6)
	v_or3_b32 v0, v8, v0, v1
	v_add_u32_e32 v180, v0, v9
	s_add_i32 s59, 0, 0x10000
	s_add_i32 s60, 0, 0x14000
	v_mbcnt_lo_u32_b32 v0, -1, 0
	v_add_u32_e32 v193, 0xffffed00, v153
	v_mov_b32_e32 v179, v167
	v_mov_b32_e32 v181, v167
	v_mov_b64_e32 v[182:183], 0xfc0
	v_mov_b64_e32 v[184:185], 0xfbf
	s_movk_i32 s58, 0x1f9
	v_add_u32_e32 v196, s59, v192
	v_add_u32_e32 v197, s60, v192
	v_add_u32_e32 v198, 0, v15
	s_mov_b32 s24, 0xbfb8aa3b
	s_mov_b64 s[26:27], 0x100ff200
	v_mov_b32_e32 v199, 0x358637bd
	s_movk_i32 s61, 0xfdf
	s_movk_i32 s68, 0xfef
	s_movk_i32 s69, 0xfff
	s_mov_b32 s28, 0x3e38aa3b
	v_mbcnt_hi_u32_b32 v200, -1, v0
	s_mov_b32 s70, 0
	s_barrier
	s_branch .LBB0_169
